# seam before the q|k|gate GEMM: waiting waves touch that GEMM's first-round weight rows into the XCD's L2 (next-phase prefetch in the barrier slack)
# baseline (speedup 1.0000x reference)
; __device__ __forceinline__ void xcd_barrier(const XcdBarrier& b) {
;     ...
;     }
;     __syncthreads();
; __global__ void __launch_bounds__(NT, 2) trunk_fwd(Args args) {
;     ...
;         { pg8::Gemm g{(const bf16*)(ws + WS_XB), (const bf16*)(ws + WS_W1T), M, NQKG, D}; pg8::StaticOrder S; S.init(M, NQKG, G, (int)blockIdx.x);
;           pg8::EpiQKG E{(bf16*)(ws + WS_U1), (const float*)(ws + WS_SSQ1), QSCALE};
;           pg8::gemm_phase<pg8::EpiQKG, pg8::StaticOrder, true, true>(lds, g, S, E); }
.Lmy_bar_go_3:
.LBB0_477:
	s_or_b64 exec, exec, s[4:5]
	v_readfirstlane_b32 s96, v184
	s_cmp_lt_u32 s96, 64
	s_cbranch_scc1 .Lwarm_skip
	s_lshr_b32 s96, s33, 3
	s_lshl_b32 s96, s96, 16
	s_add_u32 s98, s54, s96
	s_addc_u32 s99, s55, 0
	s_add_u32 s98, s98, 0xb00000
	s_addc_u32 s99, s99, 0
	v_lshlrev_b32_e32 v255, 7, v184
	global_load_dword v255, v255, s[98:99]
.Lwarm_skip:
	s_waitcnt lgkmcnt(0)
	s_barrier
